# PH9: split-K remainder tiles (float atomics into the context rows) run before the full-tile loop so the atomics drain behind the GEMM work
# speedup vs baseline: 1.0017x; 1.0017x over previous
.LBB0_1352:
	s_or_b64 exec, exec, s[0:1]
	v_readlane_b32 s0, v208, 10
	v_readlane_b32 s1, v208, 11
	s_and_b64 s[0:1], s[0:1], exec
	v_readlane_b32 s0, v207, 2
	s_cselect_b32 s6, 0x400, s0
	s_cmp_ge_i32 s97, s6
	s_movk_i32 s9, 0x4000
	s_waitcnt lgkmcnt(0)
	s_barrier
	s_branch .LBB0_1363
.Lph9_loop_entry:
	v_readlane_b32 s36, v210, 50
	s_lshl_b32 s0, s60, 1
	v_readlane_b32 s46, v210, 60
	v_readlane_b32 s47, v210, 61
	s_add_u32 s0, s46, s0
	s_addc_u32 s1, s47, 0
	v_readlane_b32 s7, v209, 2
	s_and_b32 s2, s7, 7
	s_lshr_b32 s7, s7, 3
	s_lshl_b32 s2, s2, 6
	s_or_b32 s7, s7, s2
	v_readlane_b32 s37, v210, 51
	v_readlane_b32 s38, v210, 52
	v_readlane_b32 s39, v210, 53
	v_readlane_b32 s40, v210, 54
	v_readlane_b32 s41, v210, 55
	v_readlane_b32 s42, v210, 56
	v_readlane_b32 s43, v210, 57
	v_readlane_b32 s44, v210, 58
	v_readlane_b32 s45, v210, 59
	v_readlane_b32 s48, v210, 62
	v_readlane_b32 s49, v210, 63
	v_readlane_b32 s50, v209, 0
	v_readlane_b32 s51, v209, 1
	s_branch .LBB0_1355

.Lph9_after_tail:
	s_waitcnt lgkmcnt(0)
	s_barrier
	v_readlane_b32 s0, v208, 10
	v_readlane_b32 s1, v208, 11
	s_and_b64 s[0:1], s[0:1], exec
	v_readlane_b32 s0, v207, 2
	s_cselect_b32 s6, 0x400, s0
	s_cmp_ge_i32 s97, s6
	s_cbranch_scc1 .LBB0_1365
	s_branch .Lph9_loop_entry
.Lph9_loop_exit:
	s_movk_i32 s61, 0x4000
